# rowpass: skip mid-iteration vmcnt(0) when no modulation vectors were reloaded
# speedup vs baseline: 1.0170x; 1.0012x over previous
.LBB0_536:
	s_or_b64 exec, exec, s[46:47]
	v_min_i32_e32 v0, 0x8000, v152
	v_ashrrev_i32_e32 v0, 12, v0
	s_mov_b32 s98, 0
	v_cmp_ne_u32_e32 vcc, v0, v192
	s_and_saveexec_b64 s[42:43], vcc
	s_cbranch_execz .LBB0_554
	s_mov_b32 s98, 1
	v_mul_hi_i32_i24_e32 v135, 0x9000, v0
	v_mul_i32_i24_e32 v134, 0x9000, v0
	s_and_b64 vcc, exec, s[38:39]
	v_lshl_add_u64 v[132:133], s[30:31], 0, v[134:135]
	s_cbranch_vccnz .LBB0_539
	v_mov_b32_e32 v3, v1
	v_lshl_add_u64 v[80:81], v[132:133], 0, v[2:3]
	global_load_dwordx4 v[80:83], v[80:81], off

.Lrp_lat:
	s_andn2_saveexec_b64 s[8:9], s[46:47]
	v_lshlrev_b32_e32 v132, 16, v160
	v_and_b32_e32 v133, 0xffff0000, v160
	v_lshlrev_b32_e32 v134, 16, v161
	v_and_b32_e32 v135, 0xffff0000, v161
	v_lshlrev_b32_e32 v136, 16, v158
	v_and_b32_e32 v137, 0xffff0000, v158
	v_lshlrev_b32_e32 v138, 16, v159
	v_and_b32_e32 v139, 0xffff0000, v159
	v_lshlrev_b32_e32 v144, 16, v156
	v_and_b32_e32 v145, 0xffff0000, v156
	v_lshlrev_b32_e32 v146, 16, v157
	v_and_b32_e32 v147, 0xffff0000, v157
	v_lshlrev_b32_e32 v148, 16, v154
	v_and_b32_e32 v149, 0xffff0000, v154
	v_lshlrev_b32_e32 v150, 16, v155
	v_and_b32_e32 v151, 0xffff0000, v155
	s_or_b64 exec, exec, s[8:9]
	v_mul_f32_e32 v3, v133, v133
	v_mul_f32_e32 v140, v137, v137
	v_fmac_f32_e32 v3, v132, v132
	v_fmac_f32_e32 v140, v136, v136
	v_fmac_f32_e32 v3, v134, v134
	v_fmac_f32_e32 v140, v138, v138
	v_fmac_f32_e32 v3, v135, v135
	v_fmac_f32_e32 v140, v139, v139
	v_add_f32_e32 v3, v3, v140
	v_mul_f32_e32 v140, v145, v145
	v_fmac_f32_e32 v140, v144, v144
	v_fmac_f32_e32 v140, v146, v146
	v_fmac_f32_e32 v140, v147, v147
	v_add_f32_e32 v3, v3, v140
	v_cndmask_b32_e32 v140, v0, v152, vcc
	v_mov_b32_e32 v0, s55
	v_mov_b32_e32 v142, s3
	v_cndmask_b32_e32 v141, 0, v153, vcc
	v_cndmask_b32_e32 v143, v0, v142, vcc
	v_mov_b32_e32 v0, s54
	v_mov_b32_e32 v142, s2
	v_cndmask_b32_e32 v142, v0, v142, vcc
	v_lshlrev_b64 v[140:141], 12, v[140:141]
	v_pk_mul_f32 v[194:195], v[148:149], v[148:149]
	v_lshl_add_u64 v[140:141], v[142:143], 0, v[140:141]
	v_pk_mul_f32 v[142:143], v[150:151], v[150:151]
	v_add_f32_e32 v0, v194, v195
	v_add_f32_e32 v0, v142, v0
	v_add_f32_e32 v0, v143, v0
	v_add_f32_e32 v0, v3, v0
	v_mov_b32_e32 v3, v1
	v_lshl_add_u64 v[194:195], v[140:141], 0, v[2:3]
	v_add_f32_dpp v0, v0, v0 quad_perm:[1,0,3,2] row_mask:0xf bank_mask:0xf bound_ctrl:1
	s_cmp_eq_u32 s98, 0
	s_cbranch_scc1 .Lrp_skip_w2
	s_waitcnt vmcnt(0)
.Lrp_skip_w2:
	v_pk_mul_f32 v[140:141], s[10:11], v[82:83]
	v_pk_mul_f32 v[196:197], s[18:19], v[80:81]
	v_add_f32_dpp v0, v0, v0 quad_perm:[2,3,0,1] row_mask:0xf bank_mask:0xf bound_ctrl:1
	s_nop 1
	v_add_f32_dpp v0, v0, v0 row_half_mirror row_mask:0xf bank_mask:0xf bound_ctrl:1
	s_nop 1
	v_add_f32_dpp v0, v0, v0 row_mirror row_mask:0xf bank_mask:0xf bound_ctrl:1
	s_nop 0
	v_readlane_b32 s42, v0, 16
	v_readlane_b32 s43, v0, 48
	v_readlane_b32 s8, v0, 0
	v_readlane_b32 s9, v0, 32
	v_mov_b32_e32 v142, s42
	v_mov_b32_e32 v143, s43
	v_pk_add_f32 v[142:143], s[8:9], v[142:143]
	s_nop 0
	v_add_f32_e32 v0, v142, v143
	v_fmamk_f32 v0, v0, 0x3a800000, v213
	v_rsq_f32_e32 v0, v0
	s_nop 0
	v_pk_mul_f32 v[134:135], v[134:135], v[0:1] op_sel_hi:[1,0]
	v_pk_mul_f32 v[132:133], v[132:133], v[0:1] op_sel_hi:[1,0]
	v_pk_mul_f32 v[134:135], v[6:7], v[134:135]
	v_pk_mul_f32 v[136:137], v[136:137], v[0:1] op_sel_hi:[1,0]
	v_pk_mul_f32 v[132:133], v[4:5], v[132:133]
	v_pk_fma_f32 v[142:143], v[140:141], v[134:135], v[50:51]
	v_pk_mul_f32 v[134:135], s[18:19], v[76:77]
	v_pk_mul_f32 v[138:139], v[138:139], v[0:1] op_sel_hi:[1,0]
	v_pk_mul_f32 v[136:137], v[12:13], v[136:137]
	v_pk_fma_f32 v[140:141], v[196:197], v[132:133], v[48:49]
	v_pk_mul_f32 v[132:133], s[10:11], v[78:79]
	v_pk_mul_f32 v[138:139], v[14:15], v[138:139]
	v_pk_fma_f32 v[136:137], v[134:135], v[136:137], v[44:45]
	v_pk_mul_f32 v[134:135], v[146:147], v[0:1] op_sel_hi:[1,0]
	v_pk_mul_f32 v[144:145], v[144:145], v[0:1] op_sel_hi:[1,0]
	v_pk_mul_f32 v[148:149], v[148:149], v[0:1] op_sel_hi:[1,0]
	v_pk_fma_f32 v[138:139], v[132:133], v[138:139], v[46:47]
	v_pk_mul_f32 v[132:133], s[10:11], v[74:75]
	v_pk_mul_f32 v[196:197], s[18:19], v[72:73]
	v_pk_mul_f32 v[144:145], v[20:21], v[144:145]
	v_pk_mul_f32 v[134:135], v[22:23], v[134:135]
	v_pk_mul_f32 v[146:147], s[18:19], v[68:69]
	v_pk_mul_f32 v[150:151], v[150:151], v[0:1] op_sel_hi:[1,0]
	v_pk_mul_f32 v[148:149], v[28:29], v[148:149]
	v_pk_fma_f32 v[134:135], v[132:133], v[134:135], v[42:43]
	v_pk_fma_f32 v[132:133], v[196:197], v[144:145], v[40:41]
	v_pk_mul_f32 v[144:145], s[10:11], v[70:71]
	v_pk_mul_f32 v[150:151], v[30:31], v[150:151]
	v_pk_fma_f32 v[148:149], v[146:147], v[148:149], v[36:37]
	v_pk_fma_f32 v[150:151], v[144:145], v[150:151], v[38:39]
	global_store_dwordx4 v[194:195], v[140:143], off nt
	v_mov_b64_e32 v[144:145], v[148:149]
	v_mov_b64_e32 v[146:147], v[150:151]
	global_store_dwordx4 v[194:195], v[136:139], off offset:1024 nt
	global_store_dwordx4 v[194:195], v[132:135], off offset:2048 nt
	global_store_dwordx4 v[194:195], v[148:151], off offset:3072 nt
	s_and_b64 vcc, exec, s[40:41]
	s_cbranch_vccnz .LBB0_577
